# v33: v32 + the same static priority raise for waves 4-7 in P8 (memory attention)
# speedup vs baseline: 1.0078x; 1.0015x over previous
; __device__ __forceinline__ void mem_att_unit_lds(const LAS unsigned char* kl, const LAS unsigned char* vl2, const bf16_t* qbase, const float* qgain, const float* qssq, int qnp, int nq, float scale_log2, bf16_t* obase, int lane) {
;     const int qi = lane & 31, hf = lane >> 5, qic = qi < nq ? qi : nq - 1;
;     const bf16_t* qrow = qbase + (size_t)qic * MEMW;
;     bf16x8 qf[8];
; #pragma unroll
;     for (int s = 0; s < 8; ++s) qf[s] = *(const bf16x8*)(qrow + 16 * s + 8 * hf);
;     {   float q1s = 0.f; for (int i = 0; i < qnp; ++i) q1s += qssq[qic * qnp + i];
;         const float r1 = rsqrtf(q1s * (1.f / D) + EPS);
;         float ss = 0.f;
; #pragma unroll
;         for (int s = 0; s < 8; ++s) { float f[8]; unpack8(__builtin_bit_cast(u32x4, qf[s]), f);
; #pragma unroll
;             for (int e = 0; e < 8; ++e) { const float t = f[e] * r1; ss += t * t; } }
;         ss += __shfl_xor(ss, 32);
;         const float r = rsqrtf(ss * (1.f / HD) + EPS) * r1;
; #pragma unroll
;         for (int s = 0; s < 8; ++s) { float f[8]; unpack8(__builtin_bit_cast(u32x4, qf[s]), f);
; #pragma unroll
;             for (int e = 0; e < 8; ++e) f[e] = f[e] * r * qgain[16 * s + 8 * hf + e];
;             qf[s] = __builtin_bit_cast(bf16x8, pack8(f)); } }
;     f32x16 o[4];
; #pragma unroll
;     for (int mb = 0; mb < 4; ++mb)
; #pragma unroll
;         for (int r = 0; r < 16; ++r) o[mb][r] = 0.f;
; __global__ void __launch_bounds__(512, 2) mega_fwd(Args args) {
;     ...
;     if (IN(8)) { CArgs* pa = phase_args();
;         LAS unsigned char* kl = lds; LAS unsigned char* vl2 = lds + 256 * VP;
;         for (int grp0 = bx; grp0 < 256; grp0 += G) { const int grp = (G == 256) ? (grp0 & 7) * 32 + (grp0 >> 3) : grp0; const int h = grp >> 6;
; #pragma unroll
;             for (int j = 0; j < 8; ++j) { const int id = tid + 512 * j, key = id >> 4, chk = id & 15;
;                 *(LAS bf16x8*)(kl + key * VP + chk * 16) = *(const bf16x8*)(MK + (size_t)key * MEMW + h * 128 + chk * 8);
;                 *(LAS bf16x8*)(vl2 + key * VP + chk * 16) = *(const bf16x8*)(MV + (size_t)key * MEMW + h * 128 + chk * 8); }
;             __syncthreads();
;             const int ib = (grp * 8 + wave) & 511;
;             mem_att_unit_lds(kl, vl2, QM + (size_t)(ib * 32) * MEMW + h * 128, mem_q_norm, PSSQ1 + (size_t)ib * 32 * 8, 8, 32, SCALE_LOG2, OM + (size_t)(ib * 32) * MEMW + h * 128, lane);
.LBB0_657:
	s_cmp_lt_i32 s24, 9
	s_cselect_b64 s[4:5], -1, 0
	s_cmp_gt_i32 s25, 8
	s_cselect_b64 s[6:7], -1, 0
	s_and_b64 s[4:5], s[4:5], s[6:7]
	s_andn2_b64 vcc, exec, s[4:5]
	s_cbranch_vccnz .LBB0_680
	s_mov_b64 s[8:9], s[0:1]
	s_cmp_ge_u32 s80, 4
	s_cbranch_scc0 .Lp8_prio_done
	s_setprio 1
.Lp8_prio_done:
	s_cmpk_gt_i32 s2, 0xff
	s_waitcnt vmcnt(0)
	v_and_b32_e32 v145, 31, v193
	v_lshrrev_b32_e32 v147, 5, v192
	v_lshlrev_b32_e32 v146, 1, v193
	v_lshrrev_b32_e32 v143, 4, v193
	s_cbranch_scc1 .LBB0_667
	s_load_dwordx2 s[10:11], s[8:9], 0xf8
	s_load_dwordx2 s[18:19], s[8:9], 0xa8
	v_lshlrev_b32_e32 v112, 4, v196
	v_mov_b32_e32 v113, 0
	s_mov_b64 s[6:7], 0x6380000
	s_waitcnt lgkmcnt(0)
	v_lshl_add_u64 v[0:1], s[10:11], 0, v[112:113]
	s_mov_b64 s[12:13], 0x63c0000
	v_lshl_add_u64 v[114:115], v[0:1], 0, s[6:7]
	v_lshl_add_u64 v[116:117], v[0:1], 0, s[12:13]
	v_mbcnt_lo_u32_b32 v1, -1, 0
	v_mbcnt_hi_u32_b32 v1, -1, v1
	v_and_b32_e32 v4, 64, v1
	v_xor_b32_e32 v3, 32, v1
	v_add_u32_e32 v4, 64, v4
	v_cmp_lt_i32_e32 vcc, v3, v4
	s_cmpk_eq_i32 s3, 0x100
	s_cselect_b64 s[4:5], -1, 0
	v_cndmask_b32_e32 v1, v1, v3, vcc
	s_add_i32 s6, 0, 0x11000
	v_lshlrev_b32_e32 v150, 2, v1
	v_mul_u32_u24_e32 v1, 0x110, v145
	v_lshlrev_b32_e32 v3, 4, v147
	s_add_u32 s12, s10, 0x13b00000
	v_add3_u32 v151, 0, v1, v3
	v_lshlrev_b32_e32 v4, 2, v147
	v_lshrrev_b32_e32 v1, 2, v193
	v_add_u32_e32 v8, 0x200, v193
	v_add_u32_e32 v11, 0x600, v193
	v_add_u32_e32 v13, 0xa00, v193
	v_add_u32_e32 v15, 0xe00, v193
	v_add_u32_e32 v148, 0, v112
	v_add_u32_e32 v149, s6, v112
	s_addc_u32 s13, s11, 0
	v_and_b32_e32 v112, 32, v192
	s_movk_i32 s6, 0x110
	v_and_or_b32 v1, v1, 3, v4
	v_and_b32_e32 v3, 32, v146
	v_lshlrev_b32_e32 v5, 3, v193
	v_lshlrev_b32_e32 v6, 9, v143
	v_lshrrev_b32_e32 v9, 4, v8
	v_lshrrev_b32_e32 v11, 4, v11
	v_lshrrev_b32_e32 v13, 4, v13
	v_lshrrev_b32_e32 v15, 4, v15
	s_add_u32 s14, s10, 0x14c00000
	v_lshlrev_b32_e32 v0, 9, v145
	v_lshlrev_b32_e32 v2, 3, v147
	v_lshl_add_u64 v[118:119], s[18:19], 0, v[112:113]
	v_and_b32_e32 v5, 24, v5
	v_mul_u32_u24_e32 v7, 0x110, v143
	v_lshlrev_b32_e32 v8, 9, v9
	v_mul_u32_u24_e32 v9, 0x110, v9
	v_or_b32_e32 v10, 0x8000, v6
	v_lshlrev_b32_e32 v12, 9, v11
	v_mul_u32_u24_e32 v11, 0x110, v11
	v_or_b32_e32 v14, 0x10000, v6
	v_lshlrev_b32_e32 v16, 9, v13
	v_mul_u32_u24_e32 v13, 0x110, v13
	v_or_b32_e32 v18, 0x18000, v6
	v_lshlrev_b32_e32 v20, 9, v15
	v_lshlrev_b32_e32 v112, 5, v145
	v_mad_u32_u24 v1, v1, s6, v3
	s_mov_b32 s7, 0
	s_addc_u32 s15, s11, 0
	v_mul_u32_u24_e32 v152, 0x110, v15
	v_lshl_add_u64 v[120:121], s[10:11], 0, v[112:113]
	v_add3_u32 v153, v1, v5, 0
	v_lshlrev_b32_e32 v122, 1, v6
	v_lshlrev_b32_e32 v124, 1, v8
	v_lshlrev_b32_e32 v126, 1, v10
	v_lshlrev_b32_e32 v128, 1, v12
	v_lshlrev_b32_e32 v130, 1, v14
	v_lshlrev_b32_e32 v132, 1, v16
	v_lshlrev_b32_e32 v134, 1, v18
	v_lshlrev_b32_e32 v136, 1, v20
	v_mov_b32_e32 v137, v113
	v_lshlrev_b32_e32 v112, 1, v0
	v_lshlrev_b32_e32 v138, 1, v2
	v_mov_b32_e32 v154, 0x358637bd
	s_mov_b32 s18, 0x800000
	s_mov_b32 s19, 0x3e0293ee
	v_lshlrev_b32_e32 v140, 1, v4
	v_mov_b32_e32 v123, v113
	v_add_u32_e32 v155, v148, v7
	v_add_u32_e32 v156, v149, v7
	v_mov_b32_e32 v125, v113
	v_add_u32_e32 v157, v148, v9
	v_add_u32_e32 v158, v149, v9
	v_mov_b32_e32 v127, v113
	v_mov_b32_e32 v129, v113
	v_add_u32_e32 v159, v148, v11
	v_add_u32_e32 v160, v149, v11
	v_mov_b32_e32 v131, v113
	v_mov_b32_e32 v133, v113
	v_add_u32_e32 v161, v148, v13
	v_add_u32_e32 v162, v149, v13
	v_mov_b32_e32 v135, v113
	s_mov_b32 s20, s2
	s_branch .LBB0_661

; __device__ __forceinline__ unsigned xb_ld(unsigned* p)              { return __hip_atomic_load(p, __ATOMIC_RELAXED, __HIP_MEMORY_SCOPE_AGENT); }
; __device__ __forceinline__ void xcd_barrier_complete(unsigned* bar, unsigned x, unsigned& nloc, unsigned& nx) {
;     const unsigned G = gridDim.x * gridDim.y * gridDim.z;
;     unsigned sum, cnt, mine, sp = 0u;
;     for (;;) {
;         sum = 0u; cnt = 0u; mine = 0u;
; #pragma unroll
;         for (unsigned j = 0; j < 16; ++j) { const unsigned c = xb_ld(&bar[XB_XCNT(j)]); sum += c; cnt += (c > 0u) ? 1u : 0u; mine = (j == x) ? c : mine; }
; __device__ __forceinline__ void xcd_barrier(const XcdBarrier& b) {
;     asm volatile("s_waitcnt vmcnt(0)" ::: "memory");
;     __syncthreads();
;     if (threadIdx.x == 0) {
;         unsigned* bar = b.bar;
;         __builtin_amdgcn_s_waitcnt(0);
;         unsigned nloc = b.st[0], nx = b.st[1];
;         if (nloc == 0u) { xcd_barrier_complete(bar, b.x, nloc, nx); b.st[0] = nloc; b.st[1] = nx; }
.LBB0_680:
	s_setprio 0
	s_and_b64 vcc, exec, s[42:43]
	s_cbranch_vccz .LBB0_693
	s_mov_b64 s[4:5], 0
	s_cmp_lg_u32 s26, 0
	s_mov_b64 s[6:7], 0
	s_cbranch_scc0 .LBB0_694
	s_waitcnt vmcnt(0)
	s_waitcnt vmcnt(0) lgkmcnt(0)
	s_barrier
	s_and_saveexec_b64 s[6:7], s[86:87]
	s_cbranch_execz .LBB0_1436
	s_add_i32 s8, 0, 0x23ff0
	v_mov_b32_e32 v0, s8
	s_waitcnt vmcnt(0) expcnt(0) lgkmcnt(0)
	ds_read_b32 v2, v0
	s_add_i32 s8, 0, 0x23ff4
	v_mov_b32_e32 v0, s8
	ds_read_b32 v0, v0
	s_waitcnt lgkmcnt(1)
	v_cmp_ne_u32_e32 vcc, 0, v2
	s_cbranch_vccnz .LBB0_1046
	s_load_dwordx2 s[12:13], s[82:83], 0x4
	s_add_u32 s8, s36, 0x2f000200
	s_addc_u32 s9, s37, 0
	s_add_u32 s10, s36, 0x2f000400
	s_addc_u32 s11, s37, 0
	s_waitcnt lgkmcnt(0)
	s_mul_i32 s27, s12, s3
	s_add_u32 s12, s36, 0x2f000500
	s_mul_i32 s27, s27, s13
	s_addc_u32 s13, s37, 0
	s_add_u32 s14, s36, 0x2f000600
	s_addc_u32 s15, s37, 0
	s_add_u32 s18, s36, 0x2f000700
	s_addc_u32 s19, s37, 0
	s_add_u32 s20, s36, 0x2f000800
	s_addc_u32 s21, s37, 0
	s_add_u32 s22, s36, 0x2f000900
	s_addc_u32 s23, s37, 0
	s_add_u32 s28, s36, 0x2f000a00
	s_addc_u32 s29, s37, 0
	s_add_u32 s30, s36, 0x2f000b00
	s_addc_u32 s31, s37, 0
	s_add_u32 s44, s36, 0x2f000c00
	s_addc_u32 s45, s37, 0
	s_add_u32 s46, s36, 0x2f000d00
	s_addc_u32 s47, s37, 0
	s_add_u32 s48, s36, 0x2f000e00
	s_addc_u32 s49, s37, 0
	s_add_u32 s50, s36, 0x2f000f00
	s_addc_u32 s51, s37, 0
	s_add_u32 s52, s36, 0x2f001000
	s_addc_u32 s53, s37, 0
	s_add_u32 s54, s36, 0x2f001100
	s_addc_u32 s55, s37, 0
	s_add_u32 s56, s36, 0x2f001200
	s_addc_u32 s57, s37, 0
	s_add_u32 s58, s36, 0x2f001300
	s_addc_u32 s59, s37, 0
	s_mov_b32 s33, 1
	v_mov_b32_e32 v16, 0
	s_branch .LBB0_686
